# in-proj K-loop: first iteration peeled, SrcC=0 instead of 128 v_mov zero-init per tile, first two vmcnt waits relaxed past epilogue stores; plus pipelined out-proj residual epilogue
# speedup vs baseline: 1.0100x; 1.0012x over previous
.LBB0_374:
	s_add_u32 s42, s46, 0x80
	s_addc_u32 s43, s47, 0
	s_add_u32 s46, s0, 0x100
	s_addc_u32 s47, s1, 0
	s_mov_b32 s0, 0
	s_add_i32 s97, s0, 2
	s_add_u32 s2, s42, 0x80
	s_addc_u32 s1, s43, 0
	s_add_i32 s12, 0, 0x10000
	s_cmp_eq_u32 s13, s0
	s_cselect_b32 s1, s95, s1
	s_cselect_b32 s0, s94, s2
	s_cselect_b32 s15, s55, s47
	s_cselect_b32 s14, s54, s46
	s_add_i32 s2, 0, 0x14000
	v_add_u32_e32 v140, s12, v195
	v_add_u32_e32 v174, s2, v195
	ds_read_b128 v[128:131], v140
	ds_read_b128 v[132:135], v140 offset:1024
	ds_read_b128 v[136:139], v140 offset:2048
	ds_read_b128 v[140:143], v140 offset:3072
	ds_read_b128 v[144:147], v174
	ds_read_b128 v[148:151], v174 offset:1024
	ds_read_b128 v[170:173], v174 offset:2048
	ds_read_b128 v[174:177], v174 offset:3072
	v_lshl_add_u64 v[230:231], s[42:43], 0, v[166:167]
	s_add_i32 m0, s45, 0xc000
	ds_read_b128 v[178:181], v157
	ds_read_b128 v[202:205], v157 offset:1024
	ds_read_b128 v[206:209], v157 offset:2048
	ds_read_b128 v[210:213], v157 offset:3072
	ds_read_b128 v[214:217], v157 offset:4096
	ds_read_b128 v[218:221], v157 offset:5120
	ds_read_b128 v[222:225], v157 offset:6144
	ds_read_b128 v[226:229], v157 offset:7168
	global_load_lds_dwordx4 v[230:231], off
	v_lshl_add_u64 v[230:231], s[42:43], 0, v[168:169]
	s_add_i32 m0, s45, 0xe000
	s_nop 0
	global_load_lds_dwordx4 v[230:231], off
	s_cmp_eq_u32 s18, 1
	s_cbranch_scc1 .Lpeel_strict375_1
	s_waitcnt vmcnt(16)
	s_branch .Lpeel_join375_1
.Lpeel_strict375_1:
	s_waitcnt vmcnt(8)
.Lpeel_join375_1:
	s_waitcnt lgkmcnt(0)
	s_barrier
	s_setprio 1
	s_waitcnt lgkmcnt(0)
	v_mfma_f32_16x16x32_bf16 v[120:123], v[128:131], v[178:181], 0
	v_mfma_f32_16x16x32_bf16 v[124:127], v[136:139], v[178:181], 0
	v_mfma_f32_16x16x32_bf16 v[100:103], v[128:131], v[206:209], 0
	v_mfma_f32_16x16x32_bf16 v[96:99], v[136:139], v[206:209], 0
	v_mfma_f32_16x16x32_bf16 v[84:87], v[128:131], v[214:217], 0
	v_mfma_f32_16x16x32_bf16 v[80:83], v[136:139], v[214:217], 0
	v_mfma_f32_16x16x32_bf16 v[68:71], v[128:131], v[222:225], 0
	v_mfma_f32_16x16x32_bf16 v[64:67], v[136:139], v[222:225], 0
	v_mfma_f32_16x16x32_bf16 v[120:123], v[132:135], v[202:205], v[120:123]
	v_mfma_f32_16x16x32_bf16 v[124:127], v[140:143], v[202:205], v[124:127]
	v_mfma_f32_16x16x32_bf16 v[100:103], v[132:135], v[210:213], v[100:103]
	v_mfma_f32_16x16x32_bf16 v[96:99], v[140:143], v[210:213], v[96:99]
	v_mfma_f32_16x16x32_bf16 v[84:87], v[132:135], v[218:221], v[84:87]
	v_mfma_f32_16x16x32_bf16 v[80:83], v[140:143], v[218:221], v[80:83]
	v_mfma_f32_16x16x32_bf16 v[68:71], v[132:135], v[226:229], v[68:71]
	v_mfma_f32_16x16x32_bf16 v[64:67], v[140:143], v[226:229], v[64:67]
	s_setprio 0
	s_setprio 1
	v_mfma_f32_16x16x32_bf16 v[116:119], v[144:147], v[178:181], 0
	v_mfma_f32_16x16x32_bf16 v[112:115], v[170:173], v[178:181], 0
	v_mfma_f32_16x16x32_bf16 v[108:111], v[144:147], v[206:209], 0
	v_mfma_f32_16x16x32_bf16 v[104:107], v[170:173], v[206:209], 0
	v_mfma_f32_16x16x32_bf16 v[92:95], v[144:147], v[214:217], 0
	v_mfma_f32_16x16x32_bf16 v[88:91], v[170:173], v[214:217], 0
	v_mfma_f32_16x16x32_bf16 v[76:79], v[144:147], v[222:225], 0
	v_mfma_f32_16x16x32_bf16 v[72:75], v[170:173], v[222:225], 0
	v_mfma_f32_16x16x32_bf16 v[116:119], v[148:151], v[202:205], v[116:119]
	v_mfma_f32_16x16x32_bf16 v[112:115], v[174:177], v[202:205], v[112:115]
	v_mfma_f32_16x16x32_bf16 v[108:111], v[148:151], v[210:213], v[108:111]
	v_mfma_f32_16x16x32_bf16 v[104:107], v[174:177], v[210:213], v[104:107]
	v_mfma_f32_16x16x32_bf16 v[92:95], v[148:151], v[218:221], v[92:95]
	v_mfma_f32_16x16x32_bf16 v[88:91], v[174:177], v[218:221], v[88:91]
	v_mfma_f32_16x16x32_bf16 v[76:79], v[148:151], v[226:229], v[76:79]
	v_mfma_f32_16x16x32_bf16 v[72:75], v[174:177], v[226:229], v[72:75]
	s_setprio 0
	s_barrier
	s_add_i32 s12, s12, s17
	v_lshl_add_u64 v[230:231], s[14:15], 0, v[154:155]
	s_mov_b32 m0, s12
	ds_read_b128 v[178:181], v157 offset:16384
	ds_read_b128 v[202:205], v157 offset:17408
	ds_read_b128 v[206:209], v157 offset:18432
	ds_read_b128 v[210:213], v157 offset:19456
	ds_read_b128 v[214:217], v157 offset:20480
	ds_read_b128 v[218:221], v157 offset:21504
	ds_read_b128 v[222:225], v157 offset:22528
	ds_read_b128 v[226:229], v157 offset:23552
	global_load_lds_dwordx4 v[230:231], off
	s_add_i32 m0, s12, 0x2000
	v_lshl_add_u64 v[232:233], s[14:15], 0, v[162:163]
	s_add_u32 s14, s14, s24
	s_addc_u32 s15, s15, s25
	s_add_i32 s2, s2, s17
	global_load_lds_dwordx4 v[232:233], off
	v_lshl_add_u64 v[234:235], s[14:15], 0, v[154:155]
	s_mov_b32 m0, s2
	v_lshl_add_u64 v[236:237], s[14:15], 0, v[162:163]
	global_load_lds_dwordx4 v[234:235], off
	s_add_i32 m0, s2, 0x2000
	v_lshl_add_u64 v[238:239], s[0:1], 0, v[158:159]
	global_load_lds_dwordx4 v[236:237], off
	s_mov_b32 m0, s45
	v_lshl_add_u64 v[240:241], s[0:1], 0, v[160:161]
	global_load_lds_dwordx4 v[238:239], off
	s_mov_b32 m0, s83
	s_nop 0
	global_load_lds_dwordx4 v[240:241], off
	s_cmp_eq_u32 s18, 1
	s_cbranch_scc1 .Lpeel_strict375_2
	s_waitcnt vmcnt(16)
	s_branch .Lpeel_join375_2

.Lpeel_join375_2:
	s_waitcnt lgkmcnt(0)
	s_barrier
	s_setprio 1
	s_waitcnt lgkmcnt(0)
	v_mfma_f32_16x16x32_bf16 v[52:55], v[128:131], v[178:181], 0
	v_mfma_f32_16x16x32_bf16 v[48:51], v[136:139], v[178:181], 0
	v_mfma_f32_16x16x32_bf16 v[36:39], v[128:131], v[206:209], 0
	v_mfma_f32_16x16x32_bf16 v[32:35], v[136:139], v[206:209], 0
	v_mfma_f32_16x16x32_bf16 v[20:23], v[128:131], v[214:217], 0
	v_mfma_f32_16x16x32_bf16 v[16:19], v[136:139], v[214:217], 0
	v_mfma_f32_16x16x32_bf16 v[4:7], v[128:131], v[222:225], 0
	v_mfma_f32_16x16x32_bf16 v[0:3], v[136:139], v[222:225], 0
	v_mfma_f32_16x16x32_bf16 v[52:55], v[132:135], v[202:205], v[52:55]
	v_mfma_f32_16x16x32_bf16 v[48:51], v[140:143], v[202:205], v[48:51]
	v_mfma_f32_16x16x32_bf16 v[36:39], v[132:135], v[210:213], v[36:39]
	v_mfma_f32_16x16x32_bf16 v[32:35], v[140:143], v[210:213], v[32:35]
	v_mfma_f32_16x16x32_bf16 v[20:23], v[132:135], v[218:221], v[20:23]
	v_mfma_f32_16x16x32_bf16 v[16:19], v[140:143], v[218:221], v[16:19]
	v_mfma_f32_16x16x32_bf16 v[4:7], v[132:135], v[226:229], v[4:7]
	v_mfma_f32_16x16x32_bf16 v[0:3], v[140:143], v[226:229], v[0:3]
	s_setprio 0
	s_setprio 1
	v_mfma_f32_16x16x32_bf16 v[60:63], v[144:147], v[178:181], 0
	v_mfma_f32_16x16x32_bf16 v[56:59], v[170:173], v[178:181], 0
	v_mfma_f32_16x16x32_bf16 v[44:47], v[144:147], v[206:209], 0
	v_mfma_f32_16x16x32_bf16 v[40:43], v[170:173], v[206:209], 0
	v_mfma_f32_16x16x32_bf16 v[28:31], v[144:147], v[214:217], 0
	v_mfma_f32_16x16x32_bf16 v[24:27], v[170:173], v[214:217], 0
	v_mfma_f32_16x16x32_bf16 v[12:15], v[144:147], v[222:225], 0
	v_mfma_f32_16x16x32_bf16 v[8:11], v[170:173], v[222:225], 0
	v_mfma_f32_16x16x32_bf16 v[60:63], v[148:151], v[202:205], v[60:63]
	v_mfma_f32_16x16x32_bf16 v[56:59], v[174:177], v[202:205], v[56:59]
	v_mfma_f32_16x16x32_bf16 v[44:47], v[148:151], v[210:213], v[44:47]
	v_mfma_f32_16x16x32_bf16 v[40:43], v[174:177], v[210:213], v[40:43]
	v_mfma_f32_16x16x32_bf16 v[28:31], v[148:151], v[218:221], v[28:31]
	v_mfma_f32_16x16x32_bf16 v[24:27], v[174:177], v[218:221], v[24:27]
	v_mfma_f32_16x16x32_bf16 v[12:15], v[148:151], v[226:229], v[12:15]
	v_mfma_f32_16x16x32_bf16 v[8:11], v[174:177], v[226:229], v[8:11]
	s_setprio 0
	s_barrier
	s_add_i32 s2, 0, 0x18000
	s_add_i32 s12, 0, 0x1c000
	v_add_u32_e32 v140, s2, v195
	v_add_u32_e32 v174, s12, v195
	ds_read_b128 v[128:131], v140
	ds_read_b128 v[132:135], v140 offset:1024
	ds_read_b128 v[136:139], v140 offset:2048
	ds_read_b128 v[140:143], v140 offset:3072
	ds_read_b128 v[144:147], v174
	ds_read_b128 v[148:151], v174 offset:1024
	ds_read_b128 v[170:173], v174 offset:2048
	ds_read_b128 v[174:177], v174 offset:3072
	s_add_u32 s0, s0, s8
	s_addc_u32 s1, s1, s9
	s_mov_b32 m0, s28
	v_lshl_add_u64 v[242:243], s[0:1], 0, v[158:159]
	ds_read_b128 v[178:181], v157 offset:32768
	ds_read_b128 v[202:205], v157 offset:33792
	ds_read_b128 v[206:209], v157 offset:34816
	ds_read_b128 v[210:213], v157 offset:35840
	ds_read_b128 v[214:217], v157 offset:36864
	ds_read_b128 v[218:221], v157 offset:37888
	ds_read_b128 v[222:225], v157 offset:38912
	ds_read_b128 v[226:229], v157 offset:39936
	global_load_lds_dwordx4 v[242:243], off
	v_lshl_add_u64 v[242:243], s[0:1], 0, v[160:161]
	s_mov_b32 m0, s29
	s_nop 0
	global_load_lds_dwordx4 v[242:243], off
	s_waitcnt vmcnt(8)
	s_waitcnt lgkmcnt(0)
	s_barrier
	s_setprio 1
	s_waitcnt lgkmcnt(0)
	v_mfma_f32_16x16x32_bf16 v[120:123], v[128:131], v[178:181], v[120:123]
	v_mfma_f32_16x16x32_bf16 v[124:127], v[136:139], v[178:181], v[124:127]
	v_mfma_f32_16x16x32_bf16 v[100:103], v[128:131], v[206:209], v[100:103]
	v_mfma_f32_16x16x32_bf16 v[96:99], v[136:139], v[206:209], v[96:99]
	v_mfma_f32_16x16x32_bf16 v[84:87], v[128:131], v[214:217], v[84:87]
	v_mfma_f32_16x16x32_bf16 v[80:83], v[136:139], v[214:217], v[80:83]
	v_mfma_f32_16x16x32_bf16 v[68:71], v[128:131], v[222:225], v[68:71]
	v_mfma_f32_16x16x32_bf16 v[64:67], v[136:139], v[222:225], v[64:67]
	v_mfma_f32_16x16x32_bf16 v[120:123], v[132:135], v[202:205], v[120:123]
	v_mfma_f32_16x16x32_bf16 v[124:127], v[140:143], v[202:205], v[124:127]
	v_mfma_f32_16x16x32_bf16 v[100:103], v[132:135], v[210:213], v[100:103]
	v_mfma_f32_16x16x32_bf16 v[96:99], v[140:143], v[210:213], v[96:99]
	v_mfma_f32_16x16x32_bf16 v[84:87], v[132:135], v[218:221], v[84:87]
	v_mfma_f32_16x16x32_bf16 v[80:83], v[140:143], v[218:221], v[80:83]
	v_mfma_f32_16x16x32_bf16 v[68:71], v[132:135], v[226:229], v[68:71]
	v_mfma_f32_16x16x32_bf16 v[64:67], v[140:143], v[226:229], v[64:67]
	s_setprio 0
	s_setprio 1
	v_mfma_f32_16x16x32_bf16 v[116:119], v[144:147], v[178:181], v[116:119]
	v_mfma_f32_16x16x32_bf16 v[112:115], v[170:173], v[178:181], v[112:115]
	v_mfma_f32_16x16x32_bf16 v[108:111], v[144:147], v[206:209], v[108:111]
	v_mfma_f32_16x16x32_bf16 v[104:107], v[170:173], v[206:209], v[104:107]
	v_mfma_f32_16x16x32_bf16 v[92:95], v[144:147], v[214:217], v[92:95]
	v_mfma_f32_16x16x32_bf16 v[88:91], v[170:173], v[214:217], v[88:91]
	v_mfma_f32_16x16x32_bf16 v[76:79], v[144:147], v[222:225], v[76:79]
	v_mfma_f32_16x16x32_bf16 v[72:75], v[170:173], v[222:225], v[72:75]
	v_mfma_f32_16x16x32_bf16 v[116:119], v[148:151], v[202:205], v[116:119]
	v_mfma_f32_16x16x32_bf16 v[112:115], v[174:177], v[202:205], v[112:115]
	v_mfma_f32_16x16x32_bf16 v[108:111], v[148:151], v[210:213], v[108:111]
	v_mfma_f32_16x16x32_bf16 v[104:107], v[174:177], v[210:213], v[104:107]
	v_mfma_f32_16x16x32_bf16 v[92:95], v[148:151], v[218:221], v[92:95]
	v_mfma_f32_16x16x32_bf16 v[88:91], v[174:177], v[218:221], v[88:91]
	v_mfma_f32_16x16x32_bf16 v[76:79], v[148:151], v[226:229], v[76:79]
	v_mfma_f32_16x16x32_bf16 v[72:75], v[174:177], v[226:229], v[72:75]
	s_setprio 0
	s_barrier
	s_add_i32 s0, s2, s17
	v_lshl_add_u64 v[230:231], v[230:231], 0, s[36:37]
	s_mov_b32 m0, s0
	ds_read_b128 v[178:181], v157 offset:49152
	ds_read_b128 v[202:205], v157 offset:50176
	ds_read_b128 v[206:209], v157 offset:51200
	ds_read_b128 v[210:213], v157 offset:52224
	ds_read_b128 v[214:217], v157 offset:53248
	ds_read_b128 v[218:221], v157 offset:54272
	ds_read_b128 v[222:225], v157 offset:55296
	ds_read_b128 v[226:229], v157 offset:56320
	global_load_lds_dwordx4 v[230:231], off
	v_lshl_add_u64 v[230:231], v[232:233], 0, s[36:37]
	s_add_i32 m0, s0, 0x2000
	s_add_i32 s0, s12, s17
	global_load_lds_dwordx4 v[230:231], off
	v_lshl_add_u64 v[230:231], v[234:235], 0, s[36:37]
	s_mov_b32 m0, s0
	s_nop 0
	global_load_lds_dwordx4 v[230:231], off
	v_lshl_add_u64 v[230:231], v[236:237], 0, s[36:37]
	s_add_i32 m0, s0, 0x2000
	s_nop 0
	global_load_lds_dwordx4 v[230:231], off
	v_lshl_add_u64 v[230:231], v[238:239], 0, s[36:37]
	s_mov_b32 m0, s10
	s_nop 0
	global_load_lds_dwordx4 v[230:231], off
	v_lshl_add_u64 v[230:231], v[240:241], 0, s[36:37]
	s_mov_b32 m0, s11
	s_nop 0
	global_load_lds_dwordx4 v[230:231], off
	s_waitcnt vmcnt(8)
	s_waitcnt lgkmcnt(0)
	s_barrier
	s_setprio 1
	s_waitcnt lgkmcnt(0)
	v_mfma_f32_16x16x32_bf16 v[52:55], v[128:131], v[178:181], v[52:55]
	v_mfma_f32_16x16x32_bf16 v[48:51], v[136:139], v[178:181], v[48:51]
	v_mfma_f32_16x16x32_bf16 v[36:39], v[128:131], v[206:209], v[36:39]
	v_mfma_f32_16x16x32_bf16 v[32:35], v[136:139], v[206:209], v[32:35]
	v_mfma_f32_16x16x32_bf16 v[20:23], v[128:131], v[214:217], v[20:23]
	v_mfma_f32_16x16x32_bf16 v[16:19], v[136:139], v[214:217], v[16:19]
	v_mfma_f32_16x16x32_bf16 v[4:7], v[128:131], v[222:225], v[4:7]
	v_mfma_f32_16x16x32_bf16 v[0:3], v[136:139], v[222:225], v[0:3]
	v_mfma_f32_16x16x32_bf16 v[52:55], v[132:135], v[202:205], v[52:55]
	v_mfma_f32_16x16x32_bf16 v[48:51], v[140:143], v[202:205], v[48:51]
	v_mfma_f32_16x16x32_bf16 v[36:39], v[132:135], v[210:213], v[36:39]
	v_mfma_f32_16x16x32_bf16 v[32:35], v[140:143], v[210:213], v[32:35]
	v_mfma_f32_16x16x32_bf16 v[20:23], v[132:135], v[218:221], v[20:23]
	v_mfma_f32_16x16x32_bf16 v[16:19], v[140:143], v[218:221], v[16:19]
	v_mfma_f32_16x16x32_bf16 v[4:7], v[132:135], v[226:229], v[4:7]
	v_mfma_f32_16x16x32_bf16 v[0:3], v[140:143], v[226:229], v[0:3]
	s_setprio 0
	s_setprio 1
	v_mfma_f32_16x16x32_bf16 v[60:63], v[144:147], v[178:181], v[60:63]
	v_mfma_f32_16x16x32_bf16 v[56:59], v[170:173], v[178:181], v[56:59]
	v_mfma_f32_16x16x32_bf16 v[44:47], v[144:147], v[206:209], v[44:47]
	v_mfma_f32_16x16x32_bf16 v[40:43], v[170:173], v[206:209], v[40:43]
	v_mfma_f32_16x16x32_bf16 v[28:31], v[144:147], v[214:217], v[28:31]
	v_mfma_f32_16x16x32_bf16 v[24:27], v[170:173], v[214:217], v[24:27]
	v_mfma_f32_16x16x32_bf16 v[12:15], v[144:147], v[222:225], v[12:15]
	v_mfma_f32_16x16x32_bf16 v[8:11], v[170:173], v[222:225], v[8:11]
	v_mfma_f32_16x16x32_bf16 v[60:63], v[148:151], v[202:205], v[60:63]
	v_mfma_f32_16x16x32_bf16 v[56:59], v[174:177], v[202:205], v[56:59]
	v_mfma_f32_16x16x32_bf16 v[44:47], v[148:151], v[210:213], v[44:47]
	v_mfma_f32_16x16x32_bf16 v[40:43], v[174:177], v[210:213], v[40:43]
	v_mfma_f32_16x16x32_bf16 v[28:31], v[148:151], v[218:221], v[28:31]
	v_mfma_f32_16x16x32_bf16 v[24:27], v[174:177], v[218:221], v[24:27]
	v_mfma_f32_16x16x32_bf16 v[12:15], v[148:151], v[226:229], v[12:15]
	v_mfma_f32_16x16x32_bf16 v[8:11], v[174:177], v[226:229], v[8:11]
	s_setprio 0
	s_barrier
	s_add_u32 s42, s42, 0x100
	s_addc_u32 s43, s43, 0
	s_add_u32 s46, s46, 0x100
	s_addc_u32 s47, s47, 0
	s_cmp_ge_u32 s97, s31
	s_mov_b32 s0, s97
